# grid barrier: the first workgroup of each XCD to arrive issues an early L2 write-back (the last arriver's write-back then has little left); on top of v138
# speedup vs baseline: 1.0074x; 1.0043x over previous
; __device__ __forceinline__ unsigned xb_ld(unsigned* p)              { return __hip_atomic_load(p, __ATOMIC_RELAXED, __HIP_MEMORY_SCOPE_AGENT); }
; __device__ __forceinline__ unsigned xb_add(unsigned* p, unsigned v) { return __hip_atomic_fetch_add(p, v, __ATOMIC_RELAXED, __HIP_MEMORY_SCOPE_AGENT); }
; #define XB_SPIN(cond, bar) do { unsigned _sp = 0; while (cond) { __builtin_amdgcn_s_sleep(1); \
;     if ((++_sp & 255u) == 0u) { if (xb_ld(&(bar)[XB_TMO])) break; if (_sp > XB_SPIN_CAP) { atomicAdd(&(bar)[XB_TMO], 1u); break; } } } } while (0)
; __device__ __forceinline__ void xcd_barrier(const XcdBarrier& b) {
;     ...
;     if (threadIdx.x == 0) {
;         unsigned* bar = b.bar;
;         __builtin_amdgcn_s_waitcnt(0);
;         unsigned nloc = b.st[0], nx = b.st[1];
;         if (nloc == 0u) { xcd_barrier_complete(bar, b.x, nloc, nx); b.st[0] = nloc; b.st[1] = nx; }
;         const unsigned old = xb_add(&bar[XB_XSUB(b.x)], 1u);
;         const unsigned gen = old / nloc;
;         if (old + 1u == (gen + 1u) * nloc) {
;             __builtin_amdgcn_fence(__ATOMIC_RELEASE, "agent");
;             asm volatile("s_waitcnt vmcnt(0)" ::: "memory");
;             const unsigned og = xb_add(&bar[XB_TOP], 1u);
;             const unsigned tg = og / nx;
;             if (og + 1u == (tg + 1u) * nx) xb_add(&bar[XB_TOPGEN], 1u);
;             else XB_SPIN(xb_ld(&bar[XB_TOPGEN]) == tg, bar);
;             __builtin_amdgcn_fence(__ATOMIC_ACQUIRE, "agent");
;             xb_add(&bar[XB_XGEN(b.x)], 1u);
;             asm volatile("s_waitcnt vmcnt(0)" ::: "memory");
.LBB0_121:
	s_or_b64 exec, exec, s[6:7]
	v_cvt_f32_u32_e32 v4, v2
	s_waitcnt vmcnt(0)
	v_readfirstlane_b32 s4, v3
	v_sub_u32_e32 v3, 0, v2
	v_rcp_iflag_f32_e32 v4, v4
	v_add_u32_e32 v5, s4, v1
	v_mul_f32_e32 v4, 0x4f7ffffe, v4
	v_cvt_u32_f32_e32 v4, v4
	v_mul_lo_u32 v1, v3, v4
	v_mul_hi_u32 v1, v4, v1
	v_add_u32_e32 v1, v4, v1
	v_mul_hi_u32 v1, v5, v1
	v_mul_lo_u32 v3, v1, v2
	v_sub_u32_e32 v3, v5, v3
	v_add_u32_e32 v4, 1, v1
	v_cmp_ge_u32_e32 vcc, v3, v2
	s_nop 1
	v_cndmask_b32_e32 v1, v1, v4, vcc
	v_sub_u32_e32 v4, v3, v2
	v_cndmask_b32_e32 v3, v3, v4, vcc
	v_add_u32_e32 v4, 1, v1
	v_cmp_ge_u32_e32 vcc, v3, v2
	v_add_u32_e32 v3, 1, v5
	s_nop 0
	v_cndmask_b32_e32 v1, v1, v4, vcc
	v_mul_lo_u32 v4, v2, v1
	v_cmp_eq_u32_e32 vcc, v5, v4
	s_cbranch_vccz .Lseam_nf0
	buffer_wbl2 sc1
.Lseam_nf0:
	v_add_u32_e32 v2, v4, v2
	v_cmp_ne_u32_e32 vcc, v3, v2
	s_and_saveexec_b64 s[4:5], vcc
	s_xor_b64 s[4:5], exec, s[4:5]
	s_cbranch_execz .LBB0_135
	s_waitcnt lgkmcnt(0)
	v_mov_b32_e32 v0, 0x2000
	global_load_dword v0, v0, s[2:3] offset:1024 sc1
	s_add_u32 s20, s2, 0x2400
	s_addc_u32 s21, s3, 0
	s_waitcnt vmcnt(0)
	v_cmp_eq_u32_e32 vcc, v0, v1
	s_and_saveexec_b64 s[6:7], vcc
	s_cbranch_execz .LBB0_134
	s_add_u32 s16, s74, 0x70d4200
	s_addc_u32 s17, s75, 0
	s_mov_b32 s15, 1
	s_mov_b64 s[22:23], 0
	v_mov_b32_e32 v0, 0
	s_branch .LBB0_125

; __device__ __forceinline__ unsigned xb_ld(unsigned* p)              { return __hip_atomic_load(p, __ATOMIC_RELAXED, __HIP_MEMORY_SCOPE_AGENT); }
; __device__ __forceinline__ unsigned xb_add(unsigned* p, unsigned v) { return __hip_atomic_fetch_add(p, v, __ATOMIC_RELAXED, __HIP_MEMORY_SCOPE_AGENT); }
; #define XB_SPIN(cond, bar) do { unsigned _sp = 0; while (cond) { __builtin_amdgcn_s_sleep(1); \
;     if ((++_sp & 255u) == 0u) { if (xb_ld(&(bar)[XB_TMO])) break; if (_sp > XB_SPIN_CAP) { atomicAdd(&(bar)[XB_TMO], 1u); break; } } } } while (0)
; __device__ __forceinline__ void xcd_barrier(const XcdBarrier& b) {
;     ...
;         const unsigned old = xb_add(&bar[XB_XSUB(b.x)], 1u);
;         const unsigned gen = old / nloc;
;         if (old + 1u == (gen + 1u) * nloc) {
;             __builtin_amdgcn_fence(__ATOMIC_RELEASE, "agent");
;             asm volatile("s_waitcnt vmcnt(0)" ::: "memory");
;             const unsigned og = xb_add(&bar[XB_TOP], 1u);
;             const unsigned tg = og / nx;
;             if (og + 1u == (tg + 1u) * nx) xb_add(&bar[XB_TOPGEN], 1u);
;             else XB_SPIN(xb_ld(&bar[XB_TOPGEN]) == tg, bar);
;             __builtin_amdgcn_fence(__ATOMIC_ACQUIRE, "agent");
;             xb_add(&bar[XB_XGEN(b.x)], 1u);
;             asm volatile("s_waitcnt vmcnt(0)" ::: "memory");
;         } else {
;             XB_SPIN(xb_ld(&bar[XB_XGEN(b.x)]) == gen, bar);
.Lseam_nf2:
	v_add_u32_e32 v2, v4, v2
	v_cmp_ne_u32_e32 vcc, v3, v2
	s_and_saveexec_b64 s[4:5], vcc
	s_xor_b64 s[4:5], exec, s[4:5]
	s_cbranch_execz .LBB0_349
	s_waitcnt lgkmcnt(0)
	v_mov_b32_e32 v0, 0x2000
	global_load_dword v0, v0, s[2:3] offset:1024 sc1
	s_add_u32 s10, s2, 0x2400
	s_addc_u32 s11, s3, 0
	s_waitcnt vmcnt(0)
	v_cmp_eq_u32_e32 vcc, v0, v1
	s_and_saveexec_b64 s[6:7], vcc
	s_cbranch_execz .LBB0_348
	s_add_u32 s8, s74, 0x70d4200
	s_addc_u32 s9, s75, 0
	s_mov_b32 s15, 1
	s_mov_b64 s[16:17], 0
	v_mov_b32_e32 v0, 0
	s_branch .LBB0_339

; __device__ __forceinline__ unsigned xb_ld(unsigned* p)              { return __hip_atomic_load(p, __ATOMIC_RELAXED, __HIP_MEMORY_SCOPE_AGENT); }
; __device__ __forceinline__ unsigned xb_add(unsigned* p, unsigned v) { return __hip_atomic_fetch_add(p, v, __ATOMIC_RELAXED, __HIP_MEMORY_SCOPE_AGENT); }
; #define XB_SPIN(cond, bar) do { unsigned _sp = 0; while (cond) { __builtin_amdgcn_s_sleep(1); \
;     if ((++_sp & 255u) == 0u) { if (xb_ld(&(bar)[XB_TMO])) break; if (_sp > XB_SPIN_CAP) { atomicAdd(&(bar)[XB_TMO], 1u); break; } } } } while (0)
; __device__ __forceinline__ void xcd_barrier(const XcdBarrier& b) {
;     ...
;         const unsigned old = xb_add(&bar[XB_XSUB(b.x)], 1u);
;         const unsigned gen = old / nloc;
;         if (old + 1u == (gen + 1u) * nloc) {
;             __builtin_amdgcn_fence(__ATOMIC_RELEASE, "agent");
;             asm volatile("s_waitcnt vmcnt(0)" ::: "memory");
;             const unsigned og = xb_add(&bar[XB_TOP], 1u);
;             const unsigned tg = og / nx;
;             if (og + 1u == (tg + 1u) * nx) xb_add(&bar[XB_TOPGEN], 1u);
;             else XB_SPIN(xb_ld(&bar[XB_TOPGEN]) == tg, bar);
;             __builtin_amdgcn_fence(__ATOMIC_ACQUIRE, "agent");
;             xb_add(&bar[XB_XGEN(b.x)], 1u);
;             asm volatile("s_waitcnt vmcnt(0)" ::: "memory");
;         } else {
;             XB_SPIN(xb_ld(&bar[XB_XGEN(b.x)]) == gen, bar);
.Lseam_nf9:
	v_add_u32_e32 v2, v4, v2
	v_cmp_ne_u32_e32 vcc, v3, v2
	s_and_saveexec_b64 s[4:5], vcc
	s_xor_b64 s[4:5], exec, s[4:5]
	s_cbranch_execz .LBB0_1048
	s_waitcnt lgkmcnt(0)
	v_mov_b32_e32 v0, 0x2000
	global_load_dword v0, v0, s[2:3] offset:1024 sc1
	s_add_u32 s10, s2, 0x2400
	s_addc_u32 s11, s3, 0
	s_waitcnt vmcnt(0)
	v_cmp_eq_u32_e32 vcc, v0, v1
	s_and_saveexec_b64 s[6:7], vcc
	s_cbranch_execz .LBB0_1047
	s_add_u32 s8, s74, 0x70d4200
	s_addc_u32 s9, s75, 0
	s_mov_b32 s15, 1
	s_mov_b64 s[12:13], 0
	v_mov_b32_e32 v0, 0
	s_branch .LBB0_1038
